# streaming hint also on the out-projection's f32 residual loads
# speedup vs baseline: 1.0075x; 1.0075x over previous
.LBB0_766:
	v_lshl_or_b32 v202, s56, 8, v221
	v_lshl_add_u32 v204, s10, 8, v189
	v_readlane_b32 s80, v233, 11
	v_ashrrev_i32_e32 v203, 31, v202
	v_readlane_b32 s81, v233, 12
	v_ashrrev_i32_e32 v205, 31, v204
	v_lshlrev_b64 v[128:129], 12, v[204:205]
	v_lshl_add_u64 v[206:207], v[202:203], 2, s[80:81]
	v_or_b32_e32 v212, 16, v204
	v_lshl_add_u64 v[128:129], v[206:207], 0, v[128:129]
	v_ashrrev_i32_e32 v213, 31, v212
	global_load_dwordx4 v[226:229], v[128:129], off nt
	global_load_dwordx4 v[184:187], v[128:129], off offset:64 nt
	global_load_dwordx4 v[180:183], v[128:129], off offset:512 nt
	global_load_dwordx4 v[176:179], v[128:129], off offset:576 nt
	v_lshlrev_b64 v[128:129], 12, v[212:213]
	v_or_b32_e32 v210, 32, v204
	v_lshl_add_u64 v[128:129], v[206:207], 0, v[128:129]
	v_ashrrev_i32_e32 v211, 31, v210
	global_load_dwordx4 v[172:175], v[128:129], off nt
	global_load_dwordx4 v[168:171], v[128:129], off offset:64 nt
	global_load_dwordx4 v[164:167], v[128:129], off offset:512 nt
	global_load_dwordx4 v[160:163], v[128:129], off offset:576 nt
	v_lshlrev_b64 v[128:129], 12, v[210:211]
	v_or_b32_e32 v208, 48, v204
	v_lshl_add_u64 v[128:129], v[206:207], 0, v[128:129]
	v_ashrrev_i32_e32 v209, 31, v208
	global_load_dwordx4 v[156:159], v[128:129], off nt
	global_load_dwordx4 v[152:155], v[128:129], off offset:64 nt
	global_load_dwordx4 v[148:151], v[128:129], off offset:512 nt
	global_load_dwordx4 v[144:147], v[128:129], off offset:576 nt
	v_lshlrev_b64 v[128:129], 12, v[208:209]
	v_lshl_add_u64 v[128:129], v[206:207], 0, v[128:129]
	global_load_dwordx4 v[140:143], v[128:129], off nt
	global_load_dwordx4 v[136:139], v[128:129], off offset:64 nt
	global_load_dwordx4 v[132:135], v[128:129], off offset:512 nt
	s_nop 0
	global_load_dwordx4 v[128:131], v[128:129], off offset:576 nt
	v_cndmask_b32_e64 v214, 0, 1, s[26:27]
	v_cmp_ne_u32_e64 s[10:11], 1, v214
	v_lshlrev_b64 v[214:215], 10, v[204:205]
	v_lshl_add_u64 v[214:215], v[214:215], 0, v[202:203]
	s_andn2_b64 vcc, exec, s[26:27]
	v_lshl_add_u64 v[216:217], v[214:215], 2, s[30:31]
	v_readlane_b32 s82, v233, 13
	v_readlane_b32 s83, v233, 14
	v_readlane_b32 s84, v233, 15
	v_readlane_b32 s85, v233, 16
	v_readlane_b32 s86, v233, 17
	v_readlane_b32 s87, v233, 18
	v_readlane_b32 s88, v233, 19
	v_readlane_b32 s89, v233, 20
	v_readlane_b32 s90, v233, 21
	v_readlane_b32 s91, v233, 22
	v_readlane_b32 s92, v233, 23
	v_readlane_b32 s93, v233, 24
	v_readlane_b32 s94, v233, 25
	v_readlane_b32 s95, v233, 26
	s_waitcnt vmcnt(0)
	v_pk_add_f32 v[126:127], v[126:127], v[228:229]
	v_pk_add_f32 v[124:125], v[124:125], v[226:227]
	s_cbranch_vccnz .LBB0_768
	global_store_dwordx4 v[216:217], v[124:127], off

.LBB0_806:
	s_or_b64 exec, exec, s[56:57]
	v_add_u32_e32 v130, 0x80, v204
	v_ashrrev_i32_e32 v131, 31, v130
	v_lshlrev_b64 v[64:65], 12, v[130:131]
	v_add_u32_e32 v128, 0x90, v204
	v_lshl_add_u64 v[64:65], v[206:207], 0, v[64:65]
	v_ashrrev_i32_e32 v129, 31, v128
	global_load_dwordx4 v[134:137], v[64:65], off nt
	global_load_dwordx4 v[120:123], v[64:65], off offset:64 nt
	global_load_dwordx4 v[116:119], v[64:65], off offset:512 nt
	global_load_dwordx4 v[112:115], v[64:65], off offset:576 nt
	v_lshlrev_b64 v[64:65], 12, v[128:129]
	v_add_u32_e32 v126, 0xa0, v204
	v_lshl_add_u64 v[64:65], v[206:207], 0, v[64:65]
	v_ashrrev_i32_e32 v127, 31, v126
	global_load_dwordx4 v[108:111], v[64:65], off nt
	global_load_dwordx4 v[104:107], v[64:65], off offset:64 nt
	global_load_dwordx4 v[100:103], v[64:65], off offset:512 nt
	global_load_dwordx4 v[96:99], v[64:65], off offset:576 nt
	v_lshlrev_b64 v[64:65], 12, v[126:127]
	v_add_u32_e32 v124, 0xb0, v204
	v_lshl_add_u64 v[64:65], v[206:207], 0, v[64:65]
	v_ashrrev_i32_e32 v125, 31, v124
	global_load_dwordx4 v[92:95], v[64:65], off nt
	global_load_dwordx4 v[88:91], v[64:65], off offset:64 nt
	global_load_dwordx4 v[84:87], v[64:65], off offset:512 nt
	global_load_dwordx4 v[80:83], v[64:65], off offset:576 nt
	v_lshlrev_b64 v[64:65], 12, v[124:125]
	v_lshl_add_u64 v[64:65], v[206:207], 0, v[64:65]
	global_load_dwordx4 v[76:79], v[64:65], off nt
	global_load_dwordx4 v[72:75], v[64:65], off offset:64 nt
	s_waitcnt lgkmcnt(0)
	global_load_dwordx4 v[68:71], v[64:65], off offset:512 nt
	s_nop 0
	global_load_dwordx4 v[64:67], v[64:65], off offset:576 nt
	v_lshlrev_b64 v[132:133], 10, v[130:131]
	v_lshl_add_u64 v[132:133], v[132:133], 0, v[202:203]
	s_and_b64 vcc, exec, s[10:11]
	s_waitcnt vmcnt(15)
	v_pk_add_f32 v[62:63], v[62:63], v[136:137]
	v_pk_add_f32 v[60:61], v[60:61], v[134:135]
	v_lshl_add_u64 v[134:135], v[132:133], 2, s[30:31]
	s_cbranch_vccnz .LBB0_808
	global_store_dwordx4 v[134:135], v[60:63], off
